# staging waves: decay factors computed once per column by the column-scan lanes (one exp per step and column, reciprocal for the inverse), block decay written by those lanes
# baseline (speedup 1.0000x reference)
.Lsc_G:
	v_add_u32_e32 v1, 0xffffff00, v173
	v_lshrrev_b32_e32 v2, 3, v1
	v_and_b32_e32 v3, 7, v1
	s_and_b32 s8, s4, 7
	s_bfe_u32 s10, s4, 0x20003
	s_lshr_b32 s11, s4, 7
	s_bfe_u32 s9, s4, 0x20005
	s_lshl_b32 s9, s9, 13
	v_readlane_b32 s50, v242, 0
	v_readlane_b32 s51, v242, 1
	v_readlane_b32 s16, v242, 62
	s_load_dwordx4 s[12:15], s[50:51], 0x68
	s_add_u32 s36, s90, 0x5e00000
	s_addc_u32 s37, s91, 0
	s_add_u32 s38, s90, 0x7e00000
	s_addc_u32 s39, s91, 0
	s_add_u32 s44, s90, 0x9e00000
	s_addc_u32 s45, s91, 0
	s_add_u32 s46, s90, 0x1c00000
	s_addc_u32 s47, s91, 0
	s_lshl_b32 s68, s11, 25
	s_add_u32 s69, s68, 0x13e00000
	s_add_u32 s40, s90, s69
	s_addc_u32 s41, s91, 0
	s_add_u32 s69, s68, 0x17e00000
	s_add_u32 s42, s90, s69
	s_addc_u32 s43, s91, 0
	s_lshl_b32 s68, s11, 26
	s_add_u32 s68, s68, 0xbe00000
	s_add_u32 s48, s90, s68
	s_addc_u32 s49, s91, 0
	s_cmp_eq_u32 s11, 0
	s_mov_b32 s54, 0x8000
	s_movk_i32 s55, 0x400
	s_mov_b32 s64, 0x10000
	s_cselect_b32 s54, s54, 0xffff8000
	s_cselect_b32 s55, s55, 0xfffffc00
	s_cselect_b32 s64, s64, 0xffff0000
	s_cselect_b64 vcc, -1, 0
	v_sub_u32_e32 v4, 0x1fff, v2
	s_nop 3
	v_cndmask_b32_e32 v4, v4, v2, vcc
	v_add_u32_e32 v4, s9, v4
	s_lshl_b32 s68, s8, 7
	v_lshlrev_b32_e32 v5, 10, v4
	v_lshl_add_u32 v5, v3, 3, v5
	v_add_u32_e32 v5, s68, v5
	s_lshl_b32 s69, s8, 2
	v_lshlrev_b32_e32 v6, 5, v4
	v_add_u32_e32 v6, s69, v6
	s_lshl_b32 s69, s10, 5
	s_add_i32 s69, s69, s68
	v_lshlrev_b32_e32 v9, 10, v4
	v_lshl_add_u32 v9, v3, 2, v9
	v_add_u32_e32 v9, s69, v9
	s_lshl_b32 s69, s69, 1
	v_lshlrev_b32_e32 v7, 11, v4
	v_lshl_add_u32 v7, v3, 3, v7
	v_add_u32_e32 v7, s69, v7
	v_mul_u32_u24_e32 v8, 1024, v2
	v_lshl_add_u32 v8, v3, 4, v8
	v_add_u32_e32 v138, 512, v8
	v_add_u32_e32 v140, 35328, v8
	v_add_u32_e32 v152, -4, v0
	v_lshlrev_b32_e32 v152, 13, v152
	v_add_u32_e32 v152, 107072, v152
	v_and_b32_e32 v156, 7, v2
	v_lshlrev_b32_e32 v153, 8, v156
	v_lshl_add_u32 v153, v3, 4, v153
	v_add_u32_e32 v153, v152, v153
	v_and_b32_e32 v154, 63, v1
	v_lshl_add_u32 v154, v154, 2, v152
	v_add_u32_e32 v155, 2048, v154
	v_add_u32_e32 v139, -1, v2
	v_mul_u32_u24_e32 v139, 1024, v139
	v_lshl_add_u32 v139, v3, 4, v139
	v_add_u32_e32 v141, 35328, v139
	v_add_u32_e32 v139, 512, v139
	v_cmp_eq_u32_e32 vcc, 0, v2
	s_nop 1
	v_cndmask_b32_e32 v139, v139, v152, vcc
	v_cndmask_b32_e32 v141, v141, v152, vcc
	v_lshrrev_b32_e32 v158, 3, v2
	v_lshlrev_b32_e32 v158, 8, v158
	v_lshl_add_u32 v158, v3, 4, v158
	v_and_b32_e32 v159, 63, v1
	v_lshlrev_b32_e32 v159, 2, v159
	v_add_u32_e32 v106, -4, v0
	v_lshl_add_u32 v159, v106, 8, v159
	v_add_u32_e32 v159, 33792, v159
	v_mov_b32_e32 v106, 1.0
	ds_write_b32 v155, v106
	v_add_u32_e32 v158, 32768, v158
	v_mul_u32_u24_e32 v142, 288, v3
	v_lshl_add_u32 v142, v2, 2, v142
	v_add_u32_e32 v143, 71936, v142
	v_add_u32_e32 v142, 69632, v142
	v_lshlrev_b32_e32 v11, 9, v2
	v_lshl_add_u32 v11, v3, 6, v11
	v_add_u32_e32 v11, 74240, v11
	s_lshl_b32 s69, s8, 6
	s_add_i32 s69, s69, s16
	v_lshl_add_u32 v106, v3, 2, s69
	v_lshlrev_b32_e32 v106, 2, v106
	s_waitcnt lgkmcnt(0)
	global_load_dwordx4 v[12:15], v106, s[12:13]
	global_load_dwordx4 v[16:19], v106, s[12:13] offset:128
	global_load_dwordx4 v[20:23], v106, s[14:15]
	global_load_dwordx4 v[24:27], v106, s[14:15] offset:128
	global_load_dwordx2 v[28:29], v5, s[36:37]
	global_load_dwordx2 v[30:31], v5, s[36:37] offset:64
	global_load_dwordx2 v[32:33], v5, s[38:39]
	global_load_dwordx2 v[34:35], v5, s[38:39] offset:64
	global_load_dwordx2 v[36:37], v5, s[40:41]
	global_load_dwordx2 v[38:39], v5, s[40:41] offset:64
	global_load_dwordx2 v[40:41], v5, s[42:43]
	global_load_dwordx2 v[42:43], v5, s[42:43] offset:64
	global_load_dword v44, v6, s[46:47]
	global_load_dword v45, v9, s[44:45]
	v_add_u32_e32 v5, s54, v5
	v_add_u32_e32 v6, s55, v6
	v_add_u32_e32 v9, s54, v9
	global_load_dwordx2 v[46:47], v5, s[36:37]
	global_load_dwordx2 v[48:49], v5, s[36:37] offset:64
	global_load_dwordx2 v[50:51], v5, s[38:39]
	global_load_dwordx2 v[52:53], v5, s[38:39] offset:64
	global_load_dwordx2 v[54:55], v5, s[40:41]
	global_load_dwordx2 v[56:57], v5, s[40:41] offset:64
	global_load_dwordx2 v[58:59], v5, s[42:43]
	global_load_dwordx2 v[60:61], v5, s[42:43] offset:64
	global_load_dword v62, v6, s[46:47]
	global_load_dword v63, v9, s[44:45]
	v_add_u32_e32 v5, s54, v5
	v_add_u32_e32 v6, s55, v6
	v_add_u32_e32 v9, s54, v9
	v_cmp_eq_u32_e64 s[12:13], 0, v156
	v_cmp_eq_u32_e64 s[14:15], 7, v156
	s_mov_b32 s6, 0
	v_mov_b32_e32 v144, 107024
	v_mov_b32_e32 v145, v164
	v_mov_b32_e32 v146, 0
	s_waitcnt vmcnt(10)
	v_lshlrev_b32_e32 v64, 16, v36
	v_and_b32_e32 v65, 0xffff0000, v36
	v_mul_f32_e32 v64, 0x3fb8aa3b, v64
	v_mul_f32_e32 v65, 0x3fb8aa3b, v65
	v_lshlrev_b32_e32 v66, 16, v37
	v_and_b32_e32 v67, 0xffff0000, v37
	v_mul_f32_e32 v66, 0x3fb8aa3b, v66
	v_mul_f32_e32 v67, 0x3fb8aa3b, v67
	v_lshlrev_b32_e32 v68, 16, v38
	v_and_b32_e32 v69, 0xffff0000, v38
	v_mul_f32_e32 v68, 0x3fb8aa3b, v68
	v_mul_f32_e32 v69, 0x3fb8aa3b, v69
	v_lshlrev_b32_e32 v70, 16, v39
	v_and_b32_e32 v71, 0xffff0000, v39
	v_mul_f32_e32 v70, 0x3fb8aa3b, v70
	v_mul_f32_e32 v71, 0x3fb8aa3b, v71
	ds_write_b128 v153, v[64:67]
	ds_write_b128 v153, v[68:71] offset:128
	s_waitcnt lgkmcnt(0)
	ds_read_b32 v124, v154 offset:0
	ds_read_b32 v125, v154 offset:256
	ds_read_b32 v126, v154 offset:512
	ds_read_b32 v127, v154 offset:768
	ds_read_b32 v128, v154 offset:1024
	ds_read_b32 v129, v154 offset:1280
	ds_read_b32 v130, v154 offset:1536
	ds_read_b32 v131, v154 offset:1792
	v_lshlrev_b32_e32 v108, 16, v32
	v_and_b32_e32 v109, 0xffff0000, v32
	v_lshlrev_b32_e32 v110, 16, v40
	v_and_b32_e32 v111, 0xffff0000, v40
	v_lshlrev_b32_e32 v96, 16, v28
	v_and_b32_e32 v97, 0xffff0000, v28
	v_pk_add_f32 v[112:113], v[110:111], -1.0 op_sel_hi:[1,0]
	v_pk_mul_f32 v[114:115], v[12:13], v[108:109]
	v_pk_fma_f32 v[112:113], v[20:21], v[112:113], 1.0 op_sel_hi:[1,1,0]
	v_pk_mul_f32 v[88:89], v[44:45], v[114:115] op_sel_hi:[0,1]
	v_pk_mul_f32 v[72:73], v[112:113], v[108:109]
	v_pk_mul_f32 v[80:81], v[88:89], v[110:111]
	v_lshlrev_b32_e32 v108, 16, v33
	v_and_b32_e32 v109, 0xffff0000, v33
	v_lshlrev_b32_e32 v110, 16, v41
	v_and_b32_e32 v111, 0xffff0000, v41
	v_lshlrev_b32_e32 v98, 16, v29
	v_and_b32_e32 v99, 0xffff0000, v29
	v_pk_add_f32 v[112:113], v[110:111], -1.0 op_sel_hi:[1,0]
	v_pk_mul_f32 v[114:115], v[14:15], v[108:109]
	v_pk_fma_f32 v[112:113], v[22:23], v[112:113], 1.0 op_sel_hi:[1,1,0]
	v_pk_mul_f32 v[90:91], v[44:45], v[114:115] op_sel_hi:[0,1]
	v_pk_mul_f32 v[74:75], v[112:113], v[108:109]
	v_pk_mul_f32 v[82:83], v[90:91], v[110:111]
	v_lshlrev_b32_e32 v108, 16, v34
	v_and_b32_e32 v109, 0xffff0000, v34
	v_lshlrev_b32_e32 v110, 16, v42
	v_and_b32_e32 v111, 0xffff0000, v42
	v_lshlrev_b32_e32 v100, 16, v30
	v_and_b32_e32 v101, 0xffff0000, v30
	v_pk_add_f32 v[112:113], v[110:111], -1.0 op_sel_hi:[1,0]
	v_pk_mul_f32 v[114:115], v[16:17], v[108:109]
	v_pk_fma_f32 v[112:113], v[24:25], v[112:113], 1.0 op_sel_hi:[1,1,0]
	v_pk_mul_f32 v[92:93], v[44:45], v[114:115] op_sel_hi:[0,1]
	v_pk_mul_f32 v[76:77], v[112:113], v[108:109]
	v_pk_mul_f32 v[84:85], v[92:93], v[110:111]
	v_lshlrev_b32_e32 v108, 16, v35
	v_and_b32_e32 v109, 0xffff0000, v35
	v_lshlrev_b32_e32 v110, 16, v43
	v_and_b32_e32 v111, 0xffff0000, v43
	v_lshlrev_b32_e32 v102, 16, v31
	v_and_b32_e32 v103, 0xffff0000, v31
	v_pk_add_f32 v[112:113], v[110:111], -1.0 op_sel_hi:[1,0]
	v_pk_mul_f32 v[114:115], v[18:19], v[108:109]
	v_pk_fma_f32 v[112:113], v[26:27], v[112:113], 1.0 op_sel_hi:[1,1,0]
	v_pk_mul_f32 v[94:95], v[44:45], v[114:115] op_sel_hi:[0,1]
	v_pk_mul_f32 v[78:79], v[112:113], v[108:109]
	v_pk_mul_f32 v[86:87], v[94:95], v[110:111]
	v_lshlrev_b32_e32 v104, 16, v45
	v_and_b32_e32 v105, 0xffff0000, v45
	s_waitcnt lgkmcnt(0)
	v_add_f32_e32 v125, v124, v125
	v_add_f32_e32 v126, v125, v126
	v_add_f32_e32 v127, v126, v127
	v_add_f32_e32 v128, v127, v128
	v_add_f32_e32 v129, v128, v129
	v_add_f32_e32 v130, v129, v130
	v_add_f32_e32 v131, v130, v131
	v_exp_f32_e64 v124, -v124
	v_exp_f32_e64 v125, -v125
	v_exp_f32_e64 v126, -v126
	v_exp_f32_e64 v127, -v127
	v_exp_f32_e64 v128, -v128
	v_exp_f32_e64 v129, -v129
	v_exp_f32_e64 v130, -v130
	v_exp_f32_e64 v131, -v131
	s_nop 0
	ds_write_b32 v155, v124 offset:256
	ds_write_b32 v155, v125 offset:512
	ds_write_b32 v155, v126 offset:768
	ds_write_b32 v155, v127 offset:1024
	ds_write_b32 v155, v128 offset:1280
	ds_write_b32 v155, v129 offset:1536
	ds_write_b32 v155, v130 offset:1792
	ds_write_b32 v155, v131 offset:2048
	ds_write_b32 v159, v131 offset:0
	s_waitcnt lgkmcnt(0)
	ds_read_b128 v[64:67], v153 offset:2048
	ds_read_b128 v[68:71], v153 offset:2176
	ds_read_b128 v[116:119], v153 offset:2304
	ds_read_b128 v[120:123], v153 offset:2432
	s_waitcnt lgkmcnt(0)
	v_rcp_f32_e32 v124, v116
	v_rcp_f32_e32 v125, v117
	v_rcp_f32_e32 v126, v118
	v_rcp_f32_e32 v127, v119
	v_rcp_f32_e32 v128, v120
	v_rcp_f32_e32 v129, v121
	v_rcp_f32_e32 v130, v122
	v_rcp_f32_e32 v131, v123
	s_nop 1
	v_pk_mul_f32 v[72:73], v[72:73], v[124:125]
	v_pk_mul_f32 v[80:81], v[80:81], v[124:125]
	v_pk_mul_f32 v[88:89], v[88:89], v[64:65]
	v_pk_mul_f32 v[96:97], v[96:97], v[116:117]
	v_pk_mul_f32 v[74:75], v[74:75], v[126:127]
	v_pk_mul_f32 v[82:83], v[82:83], v[126:127]
	v_pk_mul_f32 v[90:91], v[90:91], v[66:67]
	v_pk_mul_f32 v[98:99], v[98:99], v[118:119]
	v_pk_mul_f32 v[76:77], v[76:77], v[128:129]
	v_pk_mul_f32 v[84:85], v[84:85], v[128:129]
	v_pk_mul_f32 v[92:93], v[92:93], v[68:69]
	v_pk_mul_f32 v[100:101], v[100:101], v[120:121]
	v_pk_mul_f32 v[78:79], v[78:79], v[130:131]
	v_pk_mul_f32 v[86:87], v[86:87], v[130:131]
	v_pk_mul_f32 v[94:95], v[94:95], v[70:71]
	v_pk_mul_f32 v[102:103], v[102:103], v[122:123]
	ds_write_b128 v8, v[72:75] offset:0
	ds_write_b128 v8, v[76:79] offset:128
	ds_write_b128 v8, v[80:83] offset:256
	ds_write_b128 v8, v[84:87] offset:384
	ds_write2_b32 v138, v96, v97 offset0:1 offset1:3
	ds_write2_b32 v139, v88, v89 offset0:0 offset1:2
	ds_write2_b32 v138, v98, v99 offset0:65 offset1:67
	ds_write2_b32 v139, v90, v91 offset0:64 offset1:66
	ds_write2_b32 v138, v100, v101 offset0:33 offset1:35
	ds_write2_b32 v139, v92, v93 offset0:32 offset1:34
	ds_write2_b32 v138, v102, v103 offset0:97 offset1:99
	ds_write2_b32 v139, v94, v95 offset0:96 offset1:98
	ds_write2_b32 v142, v104, v105 offset1:36
	s_and_saveexec_b64 s[68:69], s[12:13]
	ds_write_b128 v158, v[88:91] offset:0
	ds_write_b128 v158, v[92:95] offset:128
	s_mov_b64 exec, s[68:69]
	global_load_dwordx2 v[28:29], v5, s[36:37]
	global_load_dwordx2 v[30:31], v5, s[36:37] offset:64
	global_load_dwordx2 v[32:33], v5, s[38:39]
	global_load_dwordx2 v[34:35], v5, s[38:39] offset:64
	global_load_dwordx2 v[36:37], v5, s[40:41]
	global_load_dwordx2 v[38:39], v5, s[40:41] offset:64
	global_load_dwordx2 v[40:41], v5, s[42:43]
	global_load_dwordx2 v[42:43], v5, s[42:43] offset:64
	global_load_dword v44, v6, s[46:47]
	global_load_dword v45, v9, s[44:45]
	v_add_u32_e32 v5, s54, v5
	v_add_u32_e32 v6, s55, v6
	v_add_u32_e32 v9, s54, v9
	s_add_i32 s6, s6, 1
	v_add_u32_e32 v146, 1, v146
	s_waitcnt lgkmcnt(0)
	ds_write_b32 v145, v146
	s_waitcnt vmcnt(10)
	v_lshlrev_b32_e32 v64, 16, v54
	v_and_b32_e32 v65, 0xffff0000, v54
	v_mul_f32_e32 v64, 0x3fb8aa3b, v64
	v_mul_f32_e32 v65, 0x3fb8aa3b, v65
	v_lshlrev_b32_e32 v66, 16, v55
	v_and_b32_e32 v67, 0xffff0000, v55
	v_mul_f32_e32 v66, 0x3fb8aa3b, v66
	v_mul_f32_e32 v67, 0x3fb8aa3b, v67
	v_lshlrev_b32_e32 v68, 16, v56
	v_and_b32_e32 v69, 0xffff0000, v56
	v_mul_f32_e32 v68, 0x3fb8aa3b, v68
	v_mul_f32_e32 v69, 0x3fb8aa3b, v69
	v_lshlrev_b32_e32 v70, 16, v57
	v_and_b32_e32 v71, 0xffff0000, v57
	v_mul_f32_e32 v70, 0x3fb8aa3b, v70
	v_mul_f32_e32 v71, 0x3fb8aa3b, v71
	ds_write_b128 v153, v[64:67]
	ds_write_b128 v153, v[68:71] offset:128
	s_waitcnt lgkmcnt(0)
	ds_read_b32 v124, v154 offset:0
	ds_read_b32 v125, v154 offset:256
	ds_read_b32 v126, v154 offset:512
	ds_read_b32 v127, v154 offset:768
	ds_read_b32 v128, v154 offset:1024
	ds_read_b32 v129, v154 offset:1280
	ds_read_b32 v130, v154 offset:1536
	ds_read_b32 v131, v154 offset:1792
	v_lshlrev_b32_e32 v108, 16, v50
	v_and_b32_e32 v109, 0xffff0000, v50
	v_lshlrev_b32_e32 v110, 16, v58
	v_and_b32_e32 v111, 0xffff0000, v58
	v_lshlrev_b32_e32 v96, 16, v46
	v_and_b32_e32 v97, 0xffff0000, v46
	v_pk_add_f32 v[112:113], v[110:111], -1.0 op_sel_hi:[1,0]
	v_pk_mul_f32 v[114:115], v[12:13], v[108:109]
	v_pk_fma_f32 v[112:113], v[20:21], v[112:113], 1.0 op_sel_hi:[1,1,0]
	v_pk_mul_f32 v[88:89], v[62:63], v[114:115] op_sel_hi:[0,1]
	v_pk_mul_f32 v[72:73], v[112:113], v[108:109]
	v_pk_mul_f32 v[80:81], v[88:89], v[110:111]
	v_lshlrev_b32_e32 v108, 16, v51
	v_and_b32_e32 v109, 0xffff0000, v51
	v_lshlrev_b32_e32 v110, 16, v59
	v_and_b32_e32 v111, 0xffff0000, v59
	v_lshlrev_b32_e32 v98, 16, v47
	v_and_b32_e32 v99, 0xffff0000, v47
	v_pk_add_f32 v[112:113], v[110:111], -1.0 op_sel_hi:[1,0]
	v_pk_mul_f32 v[114:115], v[14:15], v[108:109]
	v_pk_fma_f32 v[112:113], v[22:23], v[112:113], 1.0 op_sel_hi:[1,1,0]
	v_pk_mul_f32 v[90:91], v[62:63], v[114:115] op_sel_hi:[0,1]
	v_pk_mul_f32 v[74:75], v[112:113], v[108:109]
	v_pk_mul_f32 v[82:83], v[90:91], v[110:111]
	v_lshlrev_b32_e32 v108, 16, v52
	v_and_b32_e32 v109, 0xffff0000, v52
	v_lshlrev_b32_e32 v110, 16, v60
	v_and_b32_e32 v111, 0xffff0000, v60
	v_lshlrev_b32_e32 v100, 16, v48
	v_and_b32_e32 v101, 0xffff0000, v48
	v_pk_add_f32 v[112:113], v[110:111], -1.0 op_sel_hi:[1,0]
	v_pk_mul_f32 v[114:115], v[16:17], v[108:109]
	v_pk_fma_f32 v[112:113], v[24:25], v[112:113], 1.0 op_sel_hi:[1,1,0]
	v_pk_mul_f32 v[92:93], v[62:63], v[114:115] op_sel_hi:[0,1]
	v_pk_mul_f32 v[76:77], v[112:113], v[108:109]
	v_pk_mul_f32 v[84:85], v[92:93], v[110:111]
	v_lshlrev_b32_e32 v108, 16, v53
	v_and_b32_e32 v109, 0xffff0000, v53
	v_lshlrev_b32_e32 v110, 16, v61
	v_and_b32_e32 v111, 0xffff0000, v61
	v_lshlrev_b32_e32 v102, 16, v49
	v_and_b32_e32 v103, 0xffff0000, v49
	v_pk_add_f32 v[112:113], v[110:111], -1.0 op_sel_hi:[1,0]
	v_pk_mul_f32 v[114:115], v[18:19], v[108:109]
	v_pk_fma_f32 v[112:113], v[26:27], v[112:113], 1.0 op_sel_hi:[1,1,0]
	v_pk_mul_f32 v[94:95], v[62:63], v[114:115] op_sel_hi:[0,1]
	v_pk_mul_f32 v[78:79], v[112:113], v[108:109]
	v_pk_mul_f32 v[86:87], v[94:95], v[110:111]
	v_lshlrev_b32_e32 v104, 16, v63
	v_and_b32_e32 v105, 0xffff0000, v63
	s_waitcnt lgkmcnt(0)
	v_add_f32_e32 v125, v124, v125
	v_add_f32_e32 v126, v125, v126
	v_add_f32_e32 v127, v126, v127
	v_add_f32_e32 v128, v127, v128
	v_add_f32_e32 v129, v128, v129
	v_add_f32_e32 v130, v129, v130
	v_add_f32_e32 v131, v130, v131
	v_exp_f32_e64 v124, -v124
	v_exp_f32_e64 v125, -v125
	v_exp_f32_e64 v126, -v126
	v_exp_f32_e64 v127, -v127
	v_exp_f32_e64 v128, -v128
	v_exp_f32_e64 v129, -v129
	v_exp_f32_e64 v130, -v130
	v_exp_f32_e64 v131, -v131
	s_nop 0
	ds_write_b32 v155, v124 offset:256
	ds_write_b32 v155, v125 offset:512
	ds_write_b32 v155, v126 offset:768
	ds_write_b32 v155, v127 offset:1024
	ds_write_b32 v155, v128 offset:1280
	ds_write_b32 v155, v129 offset:1536
	ds_write_b32 v155, v130 offset:1792
	ds_write_b32 v155, v131 offset:2048
	ds_write_b32 v159, v131 offset:34816
	s_waitcnt lgkmcnt(0)
	ds_read_b128 v[64:67], v153 offset:2048
	ds_read_b128 v[68:71], v153 offset:2176
	ds_read_b128 v[116:119], v153 offset:2304
	ds_read_b128 v[120:123], v153 offset:2432
	s_waitcnt lgkmcnt(0)
	v_rcp_f32_e32 v124, v116
	v_rcp_f32_e32 v125, v117
	v_rcp_f32_e32 v126, v118
	v_rcp_f32_e32 v127, v119
	v_rcp_f32_e32 v128, v120
	v_rcp_f32_e32 v129, v121
	v_rcp_f32_e32 v130, v122
	v_rcp_f32_e32 v131, v123
	s_nop 1
	v_pk_mul_f32 v[72:73], v[72:73], v[124:125]
	v_pk_mul_f32 v[80:81], v[80:81], v[124:125]
	v_pk_mul_f32 v[88:89], v[88:89], v[64:65]
	v_pk_mul_f32 v[96:97], v[96:97], v[116:117]
	v_pk_mul_f32 v[74:75], v[74:75], v[126:127]
	v_pk_mul_f32 v[82:83], v[82:83], v[126:127]
	v_pk_mul_f32 v[90:91], v[90:91], v[66:67]
	v_pk_mul_f32 v[98:99], v[98:99], v[118:119]
	v_pk_mul_f32 v[76:77], v[76:77], v[128:129]
	v_pk_mul_f32 v[84:85], v[84:85], v[128:129]
	v_pk_mul_f32 v[92:93], v[92:93], v[68:69]
	v_pk_mul_f32 v[100:101], v[100:101], v[120:121]
	v_pk_mul_f32 v[78:79], v[78:79], v[130:131]
	v_pk_mul_f32 v[86:87], v[86:87], v[130:131]
	v_pk_mul_f32 v[94:95], v[94:95], v[70:71]
	v_pk_mul_f32 v[102:103], v[102:103], v[122:123]
	ds_write_b128 v8, v[72:75] offset:34816
	ds_write_b128 v8, v[76:79] offset:34944
	ds_write_b128 v8, v[80:83] offset:35072
	ds_write_b128 v8, v[84:87] offset:35200
	ds_write2_b32 v140, v96, v97 offset0:1 offset1:3
	ds_write2_b32 v141, v88, v89 offset0:0 offset1:2
	ds_write2_b32 v140, v98, v99 offset0:65 offset1:67
	ds_write2_b32 v141, v90, v91 offset0:64 offset1:66
	ds_write2_b32 v140, v100, v101 offset0:33 offset1:35
	ds_write2_b32 v141, v92, v93 offset0:32 offset1:34
	ds_write2_b32 v140, v102, v103 offset0:97 offset1:99
	ds_write2_b32 v141, v94, v95 offset0:96 offset1:98
	ds_write2_b32 v143, v104, v105 offset1:36
	s_and_saveexec_b64 s[68:69], s[12:13]
	ds_write_b128 v158, v[88:91] offset:34816
	ds_write_b128 v158, v[92:95] offset:34944
	s_mov_b64 exec, s[68:69]
	global_load_dwordx2 v[46:47], v5, s[36:37]
	global_load_dwordx2 v[48:49], v5, s[36:37] offset:64
	global_load_dwordx2 v[50:51], v5, s[38:39]
	global_load_dwordx2 v[52:53], v5, s[38:39] offset:64
	global_load_dwordx2 v[54:55], v5, s[40:41]
	global_load_dwordx2 v[56:57], v5, s[40:41] offset:64
	global_load_dwordx2 v[58:59], v5, s[42:43]
	global_load_dwordx2 v[60:61], v5, s[42:43] offset:64
	global_load_dword v62, v6, s[46:47]
	global_load_dword v63, v9, s[44:45]
	v_add_u32_e32 v5, s54, v5
	v_add_u32_e32 v6, s55, v6
	v_add_u32_e32 v9, s54, v9
	s_add_i32 s6, s6, 1
	v_add_u32_e32 v146, 1, v146
	s_waitcnt lgkmcnt(0)
	ds_write_b32 v145, v146

.Lsc_G_gom0:
	s_waitcnt vmcnt(10)
	v_lshlrev_b32_e32 v64, 16, v36
	v_and_b32_e32 v65, 0xffff0000, v36
	v_mul_f32_e32 v64, 0x3fb8aa3b, v64
	v_mul_f32_e32 v65, 0x3fb8aa3b, v65
	v_lshlrev_b32_e32 v66, 16, v37
	v_and_b32_e32 v67, 0xffff0000, v37
	v_mul_f32_e32 v66, 0x3fb8aa3b, v66
	v_mul_f32_e32 v67, 0x3fb8aa3b, v67
	v_lshlrev_b32_e32 v68, 16, v38
	v_and_b32_e32 v69, 0xffff0000, v38
	v_mul_f32_e32 v68, 0x3fb8aa3b, v68
	v_mul_f32_e32 v69, 0x3fb8aa3b, v69
	v_lshlrev_b32_e32 v70, 16, v39
	v_and_b32_e32 v71, 0xffff0000, v39
	v_mul_f32_e32 v70, 0x3fb8aa3b, v70
	v_mul_f32_e32 v71, 0x3fb8aa3b, v71
	ds_write_b128 v153, v[64:67]
	ds_write_b128 v153, v[68:71] offset:128
	s_waitcnt lgkmcnt(0)
	ds_read_b32 v124, v154 offset:0
	ds_read_b32 v125, v154 offset:256
	ds_read_b32 v126, v154 offset:512
	ds_read_b32 v127, v154 offset:768
	ds_read_b32 v128, v154 offset:1024
	ds_read_b32 v129, v154 offset:1280
	ds_read_b32 v130, v154 offset:1536
	ds_read_b32 v131, v154 offset:1792
	v_lshlrev_b32_e32 v108, 16, v32
	v_and_b32_e32 v109, 0xffff0000, v32
	v_lshlrev_b32_e32 v110, 16, v40
	v_and_b32_e32 v111, 0xffff0000, v40
	v_lshlrev_b32_e32 v96, 16, v28
	v_and_b32_e32 v97, 0xffff0000, v28
	v_pk_add_f32 v[112:113], v[110:111], -1.0 op_sel_hi:[1,0]
	v_pk_mul_f32 v[114:115], v[12:13], v[108:109]
	v_pk_fma_f32 v[112:113], v[20:21], v[112:113], 1.0 op_sel_hi:[1,1,0]
	v_pk_mul_f32 v[88:89], v[44:45], v[114:115] op_sel_hi:[0,1]
	v_pk_mul_f32 v[72:73], v[112:113], v[108:109]
	v_pk_mul_f32 v[80:81], v[88:89], v[110:111]
	v_lshlrev_b32_e32 v108, 16, v33
	v_and_b32_e32 v109, 0xffff0000, v33
	v_lshlrev_b32_e32 v110, 16, v41
	v_and_b32_e32 v111, 0xffff0000, v41
	v_lshlrev_b32_e32 v98, 16, v29
	v_and_b32_e32 v99, 0xffff0000, v29
	v_pk_add_f32 v[112:113], v[110:111], -1.0 op_sel_hi:[1,0]
	v_pk_mul_f32 v[114:115], v[14:15], v[108:109]
	v_pk_fma_f32 v[112:113], v[22:23], v[112:113], 1.0 op_sel_hi:[1,1,0]
	v_pk_mul_f32 v[90:91], v[44:45], v[114:115] op_sel_hi:[0,1]
	v_pk_mul_f32 v[74:75], v[112:113], v[108:109]
	v_pk_mul_f32 v[82:83], v[90:91], v[110:111]
	v_lshlrev_b32_e32 v108, 16, v34
	v_and_b32_e32 v109, 0xffff0000, v34
	v_lshlrev_b32_e32 v110, 16, v42
	v_and_b32_e32 v111, 0xffff0000, v42
	v_lshlrev_b32_e32 v100, 16, v30
	v_and_b32_e32 v101, 0xffff0000, v30
	v_pk_add_f32 v[112:113], v[110:111], -1.0 op_sel_hi:[1,0]
	v_pk_mul_f32 v[114:115], v[16:17], v[108:109]
	v_pk_fma_f32 v[112:113], v[24:25], v[112:113], 1.0 op_sel_hi:[1,1,0]
	v_pk_mul_f32 v[92:93], v[44:45], v[114:115] op_sel_hi:[0,1]
	v_pk_mul_f32 v[76:77], v[112:113], v[108:109]
	v_pk_mul_f32 v[84:85], v[92:93], v[110:111]
	v_lshlrev_b32_e32 v108, 16, v35
	v_and_b32_e32 v109, 0xffff0000, v35
	v_lshlrev_b32_e32 v110, 16, v43
	v_and_b32_e32 v111, 0xffff0000, v43
	v_lshlrev_b32_e32 v102, 16, v31
	v_and_b32_e32 v103, 0xffff0000, v31
	v_pk_add_f32 v[112:113], v[110:111], -1.0 op_sel_hi:[1,0]
	v_pk_mul_f32 v[114:115], v[18:19], v[108:109]
	v_pk_fma_f32 v[112:113], v[26:27], v[112:113], 1.0 op_sel_hi:[1,1,0]
	v_pk_mul_f32 v[94:95], v[44:45], v[114:115] op_sel_hi:[0,1]
	v_pk_mul_f32 v[78:79], v[112:113], v[108:109]
	v_pk_mul_f32 v[86:87], v[94:95], v[110:111]
	v_lshlrev_b32_e32 v104, 16, v45
	v_and_b32_e32 v105, 0xffff0000, v45
	s_waitcnt lgkmcnt(0)
	v_add_f32_e32 v125, v124, v125
	v_add_f32_e32 v126, v125, v126
	v_add_f32_e32 v127, v126, v127
	v_add_f32_e32 v128, v127, v128
	v_add_f32_e32 v129, v128, v129
	v_add_f32_e32 v130, v129, v130
	v_add_f32_e32 v131, v130, v131
	v_exp_f32_e64 v124, -v124
	v_exp_f32_e64 v125, -v125
	v_exp_f32_e64 v126, -v126
	v_exp_f32_e64 v127, -v127
	v_exp_f32_e64 v128, -v128
	v_exp_f32_e64 v129, -v129
	v_exp_f32_e64 v130, -v130
	v_exp_f32_e64 v131, -v131
	s_nop 0
	ds_write_b32 v155, v124 offset:256
	ds_write_b32 v155, v125 offset:512
	ds_write_b32 v155, v126 offset:768
	ds_write_b32 v155, v127 offset:1024
	ds_write_b32 v155, v128 offset:1280
	ds_write_b32 v155, v129 offset:1536
	ds_write_b32 v155, v130 offset:1792
	ds_write_b32 v155, v131 offset:2048
	ds_write_b32 v159, v131 offset:0
	s_waitcnt lgkmcnt(0)
	ds_read_b128 v[64:67], v153 offset:2048
	ds_read_b128 v[68:71], v153 offset:2176
	ds_read_b128 v[116:119], v153 offset:2304
	ds_read_b128 v[120:123], v153 offset:2432
	s_waitcnt lgkmcnt(0)
	v_rcp_f32_e32 v124, v116
	v_rcp_f32_e32 v125, v117
	v_rcp_f32_e32 v126, v118
	v_rcp_f32_e32 v127, v119
	v_rcp_f32_e32 v128, v120
	v_rcp_f32_e32 v129, v121
	v_rcp_f32_e32 v130, v122
	v_rcp_f32_e32 v131, v123
	s_nop 1
	v_pk_mul_f32 v[72:73], v[72:73], v[124:125]
	v_pk_mul_f32 v[80:81], v[80:81], v[124:125]
	v_pk_mul_f32 v[88:89], v[88:89], v[64:65]
	v_pk_mul_f32 v[96:97], v[96:97], v[116:117]
	v_pk_mul_f32 v[74:75], v[74:75], v[126:127]
	v_pk_mul_f32 v[82:83], v[82:83], v[126:127]
	v_pk_mul_f32 v[90:91], v[90:91], v[66:67]
	v_pk_mul_f32 v[98:99], v[98:99], v[118:119]
	v_pk_mul_f32 v[76:77], v[76:77], v[128:129]
	v_pk_mul_f32 v[84:85], v[84:85], v[128:129]
	v_pk_mul_f32 v[92:93], v[92:93], v[68:69]
	v_pk_mul_f32 v[100:101], v[100:101], v[120:121]
	v_pk_mul_f32 v[78:79], v[78:79], v[130:131]
	v_pk_mul_f32 v[86:87], v[86:87], v[130:131]
	v_pk_mul_f32 v[94:95], v[94:95], v[70:71]
	v_pk_mul_f32 v[102:103], v[102:103], v[122:123]
	ds_write_b128 v8, v[72:75] offset:0
	ds_write_b128 v8, v[76:79] offset:128
	ds_write_b128 v8, v[80:83] offset:256
	ds_write_b128 v8, v[84:87] offset:384
	ds_write2_b32 v138, v96, v97 offset0:1 offset1:3
	ds_write2_b32 v139, v88, v89 offset0:0 offset1:2
	ds_write2_b32 v138, v98, v99 offset0:65 offset1:67
	ds_write2_b32 v139, v90, v91 offset0:64 offset1:66
	ds_write2_b32 v138, v100, v101 offset0:33 offset1:35
	ds_write2_b32 v139, v92, v93 offset0:32 offset1:34
	ds_write2_b32 v138, v102, v103 offset0:97 offset1:99
	ds_write2_b32 v139, v94, v95 offset0:96 offset1:98
	ds_write2_b32 v142, v104, v105 offset1:36
	s_and_saveexec_b64 s[68:69], s[12:13]
	ds_write_b128 v158, v[88:91] offset:0
	ds_write_b128 v158, v[92:95] offset:128
	s_mov_b64 exec, s[68:69]
	global_load_dwordx2 v[28:29], v5, s[36:37]
	global_load_dwordx2 v[30:31], v5, s[36:37] offset:64
	global_load_dwordx2 v[32:33], v5, s[38:39]
	global_load_dwordx2 v[34:35], v5, s[38:39] offset:64
	global_load_dwordx2 v[36:37], v5, s[40:41]
	global_load_dwordx2 v[38:39], v5, s[40:41] offset:64
	global_load_dwordx2 v[40:41], v5, s[42:43]
	global_load_dwordx2 v[42:43], v5, s[42:43] offset:64
	global_load_dword v44, v6, s[46:47]
	global_load_dword v45, v9, s[44:45]
	v_add_u32_e32 v5, s54, v5
	v_add_u32_e32 v6, s55, v6
	v_add_u32_e32 v9, s54, v9
	ds_read_b128 v[120:123], v11 offset:0
	ds_read_b128 v[124:127], v11 offset:16
	ds_read_b128 v[128:131], v11 offset:32
	ds_read_b128 v[132:135], v11 offset:48
	s_waitcnt lgkmcnt(0)
	v_add_f32_e32 v120, v120, v121
	v_add_f32_e32 v122, v122, v123
	v_add_f32_e32 v124, v124, v125
	v_add_f32_e32 v126, v126, v127
	v_add_f32_e32 v120, v120, v122
	v_add_f32_e32 v124, v124, v126
	v_add_f32_e32 v136, v120, v124
	v_add_f32_e32 v128, v128, v129
	v_add_f32_e32 v130, v130, v131
	v_add_f32_e32 v132, v132, v133
	v_add_f32_e32 v134, v134, v135
	v_add_f32_e32 v128, v128, v130
	v_add_f32_e32 v132, v132, v134
	v_add_f32_e32 v137, v128, v132
	global_store_dwordx2 v7, v[136:137], s[48:49]
	v_add_u32_e32 v7, s64, v7
	s_add_i32 s6, s6, 1
	v_add_u32_e32 v146, 1, v146
	s_waitcnt lgkmcnt(0)
	ds_write_b32 v145, v146
	s_sub_u32 s65, s6, 1
	s_mov_b32 s69, 0x100000

.Lsc_G_gom1:
	s_waitcnt vmcnt(10)
	v_lshlrev_b32_e32 v64, 16, v54
	v_and_b32_e32 v65, 0xffff0000, v54
	v_mul_f32_e32 v64, 0x3fb8aa3b, v64
	v_mul_f32_e32 v65, 0x3fb8aa3b, v65
	v_lshlrev_b32_e32 v66, 16, v55
	v_and_b32_e32 v67, 0xffff0000, v55
	v_mul_f32_e32 v66, 0x3fb8aa3b, v66
	v_mul_f32_e32 v67, 0x3fb8aa3b, v67
	v_lshlrev_b32_e32 v68, 16, v56
	v_and_b32_e32 v69, 0xffff0000, v56
	v_mul_f32_e32 v68, 0x3fb8aa3b, v68
	v_mul_f32_e32 v69, 0x3fb8aa3b, v69
	v_lshlrev_b32_e32 v70, 16, v57
	v_and_b32_e32 v71, 0xffff0000, v57
	v_mul_f32_e32 v70, 0x3fb8aa3b, v70
	v_mul_f32_e32 v71, 0x3fb8aa3b, v71
	ds_write_b128 v153, v[64:67]
	ds_write_b128 v153, v[68:71] offset:128
	s_waitcnt lgkmcnt(0)
	ds_read_b32 v124, v154 offset:0
	ds_read_b32 v125, v154 offset:256
	ds_read_b32 v126, v154 offset:512
	ds_read_b32 v127, v154 offset:768
	ds_read_b32 v128, v154 offset:1024
	ds_read_b32 v129, v154 offset:1280
	ds_read_b32 v130, v154 offset:1536
	ds_read_b32 v131, v154 offset:1792
	v_lshlrev_b32_e32 v108, 16, v50
	v_and_b32_e32 v109, 0xffff0000, v50
	v_lshlrev_b32_e32 v110, 16, v58
	v_and_b32_e32 v111, 0xffff0000, v58
	v_lshlrev_b32_e32 v96, 16, v46
	v_and_b32_e32 v97, 0xffff0000, v46
	v_pk_add_f32 v[112:113], v[110:111], -1.0 op_sel_hi:[1,0]
	v_pk_mul_f32 v[114:115], v[12:13], v[108:109]
	v_pk_fma_f32 v[112:113], v[20:21], v[112:113], 1.0 op_sel_hi:[1,1,0]
	v_pk_mul_f32 v[88:89], v[62:63], v[114:115] op_sel_hi:[0,1]
	v_pk_mul_f32 v[72:73], v[112:113], v[108:109]
	v_pk_mul_f32 v[80:81], v[88:89], v[110:111]
	v_lshlrev_b32_e32 v108, 16, v51
	v_and_b32_e32 v109, 0xffff0000, v51
	v_lshlrev_b32_e32 v110, 16, v59
	v_and_b32_e32 v111, 0xffff0000, v59
	v_lshlrev_b32_e32 v98, 16, v47
	v_and_b32_e32 v99, 0xffff0000, v47
	v_pk_add_f32 v[112:113], v[110:111], -1.0 op_sel_hi:[1,0]
	v_pk_mul_f32 v[114:115], v[14:15], v[108:109]
	v_pk_fma_f32 v[112:113], v[22:23], v[112:113], 1.0 op_sel_hi:[1,1,0]
	v_pk_mul_f32 v[90:91], v[62:63], v[114:115] op_sel_hi:[0,1]
	v_pk_mul_f32 v[74:75], v[112:113], v[108:109]
	v_pk_mul_f32 v[82:83], v[90:91], v[110:111]
	v_lshlrev_b32_e32 v108, 16, v52
	v_and_b32_e32 v109, 0xffff0000, v52
	v_lshlrev_b32_e32 v110, 16, v60
	v_and_b32_e32 v111, 0xffff0000, v60
	v_lshlrev_b32_e32 v100, 16, v48
	v_and_b32_e32 v101, 0xffff0000, v48
	v_pk_add_f32 v[112:113], v[110:111], -1.0 op_sel_hi:[1,0]
	v_pk_mul_f32 v[114:115], v[16:17], v[108:109]
	v_pk_fma_f32 v[112:113], v[24:25], v[112:113], 1.0 op_sel_hi:[1,1,0]
	v_pk_mul_f32 v[92:93], v[62:63], v[114:115] op_sel_hi:[0,1]
	v_pk_mul_f32 v[76:77], v[112:113], v[108:109]
	v_pk_mul_f32 v[84:85], v[92:93], v[110:111]
	v_lshlrev_b32_e32 v108, 16, v53
	v_and_b32_e32 v109, 0xffff0000, v53
	v_lshlrev_b32_e32 v110, 16, v61
	v_and_b32_e32 v111, 0xffff0000, v61
	v_lshlrev_b32_e32 v102, 16, v49
	v_and_b32_e32 v103, 0xffff0000, v49
	v_pk_add_f32 v[112:113], v[110:111], -1.0 op_sel_hi:[1,0]
	v_pk_mul_f32 v[114:115], v[18:19], v[108:109]
	v_pk_fma_f32 v[112:113], v[26:27], v[112:113], 1.0 op_sel_hi:[1,1,0]
	v_pk_mul_f32 v[94:95], v[62:63], v[114:115] op_sel_hi:[0,1]
	v_pk_mul_f32 v[78:79], v[112:113], v[108:109]
	v_pk_mul_f32 v[86:87], v[94:95], v[110:111]
	v_lshlrev_b32_e32 v104, 16, v63
	v_and_b32_e32 v105, 0xffff0000, v63
	s_waitcnt lgkmcnt(0)
	v_add_f32_e32 v125, v124, v125
	v_add_f32_e32 v126, v125, v126
	v_add_f32_e32 v127, v126, v127
	v_add_f32_e32 v128, v127, v128
	v_add_f32_e32 v129, v128, v129
	v_add_f32_e32 v130, v129, v130
	v_add_f32_e32 v131, v130, v131
	v_exp_f32_e64 v124, -v124
	v_exp_f32_e64 v125, -v125
	v_exp_f32_e64 v126, -v126
	v_exp_f32_e64 v127, -v127
	v_exp_f32_e64 v128, -v128
	v_exp_f32_e64 v129, -v129
	v_exp_f32_e64 v130, -v130
	v_exp_f32_e64 v131, -v131
	s_nop 0
	ds_write_b32 v155, v124 offset:256
	ds_write_b32 v155, v125 offset:512
	ds_write_b32 v155, v126 offset:768
	ds_write_b32 v155, v127 offset:1024
	ds_write_b32 v155, v128 offset:1280
	ds_write_b32 v155, v129 offset:1536
	ds_write_b32 v155, v130 offset:1792
	ds_write_b32 v155, v131 offset:2048
	ds_write_b32 v159, v131 offset:34816
	s_waitcnt lgkmcnt(0)
	ds_read_b128 v[64:67], v153 offset:2048
	ds_read_b128 v[68:71], v153 offset:2176
	ds_read_b128 v[116:119], v153 offset:2304
	ds_read_b128 v[120:123], v153 offset:2432
	s_waitcnt lgkmcnt(0)
	v_rcp_f32_e32 v124, v116
	v_rcp_f32_e32 v125, v117
	v_rcp_f32_e32 v126, v118
	v_rcp_f32_e32 v127, v119
	v_rcp_f32_e32 v128, v120
	v_rcp_f32_e32 v129, v121
	v_rcp_f32_e32 v130, v122
	v_rcp_f32_e32 v131, v123
	s_nop 1
	v_pk_mul_f32 v[72:73], v[72:73], v[124:125]
	v_pk_mul_f32 v[80:81], v[80:81], v[124:125]
	v_pk_mul_f32 v[88:89], v[88:89], v[64:65]
	v_pk_mul_f32 v[96:97], v[96:97], v[116:117]
	v_pk_mul_f32 v[74:75], v[74:75], v[126:127]
	v_pk_mul_f32 v[82:83], v[82:83], v[126:127]
	v_pk_mul_f32 v[90:91], v[90:91], v[66:67]
	v_pk_mul_f32 v[98:99], v[98:99], v[118:119]
	v_pk_mul_f32 v[76:77], v[76:77], v[128:129]
	v_pk_mul_f32 v[84:85], v[84:85], v[128:129]
	v_pk_mul_f32 v[92:93], v[92:93], v[68:69]
	v_pk_mul_f32 v[100:101], v[100:101], v[120:121]
	v_pk_mul_f32 v[78:79], v[78:79], v[130:131]
	v_pk_mul_f32 v[86:87], v[86:87], v[130:131]
	v_pk_mul_f32 v[94:95], v[94:95], v[70:71]
	v_pk_mul_f32 v[102:103], v[102:103], v[122:123]
	ds_write_b128 v8, v[72:75] offset:34816
	ds_write_b128 v8, v[76:79] offset:34944
	ds_write_b128 v8, v[80:83] offset:35072
	ds_write_b128 v8, v[84:87] offset:35200
	ds_write2_b32 v140, v96, v97 offset0:1 offset1:3
	ds_write2_b32 v141, v88, v89 offset0:0 offset1:2
	ds_write2_b32 v140, v98, v99 offset0:65 offset1:67
	ds_write2_b32 v141, v90, v91 offset0:64 offset1:66
	ds_write2_b32 v140, v100, v101 offset0:33 offset1:35
	ds_write2_b32 v141, v92, v93 offset0:32 offset1:34
	ds_write2_b32 v140, v102, v103 offset0:97 offset1:99
	ds_write2_b32 v141, v94, v95 offset0:96 offset1:98
	ds_write2_b32 v143, v104, v105 offset1:36
	s_and_saveexec_b64 s[68:69], s[12:13]
	ds_write_b128 v158, v[88:91] offset:34816
	ds_write_b128 v158, v[92:95] offset:34944
	s_mov_b64 exec, s[68:69]
	global_load_dwordx2 v[46:47], v5, s[36:37]
	global_load_dwordx2 v[48:49], v5, s[36:37] offset:64
	global_load_dwordx2 v[50:51], v5, s[38:39]
	global_load_dwordx2 v[52:53], v5, s[38:39] offset:64
	global_load_dwordx2 v[54:55], v5, s[40:41]
	global_load_dwordx2 v[56:57], v5, s[40:41] offset:64
	global_load_dwordx2 v[58:59], v5, s[42:43]
	global_load_dwordx2 v[60:61], v5, s[42:43] offset:64
	global_load_dword v62, v6, s[46:47]
	global_load_dword v63, v9, s[44:45]
	v_add_u32_e32 v5, s54, v5
	v_add_u32_e32 v6, s55, v6
	v_add_u32_e32 v9, s54, v9
	ds_read_b128 v[120:123], v11 offset:16384
	ds_read_b128 v[124:127], v11 offset:16400
	ds_read_b128 v[128:131], v11 offset:16416
	ds_read_b128 v[132:135], v11 offset:16432
	s_waitcnt lgkmcnt(0)
	v_add_f32_e32 v120, v120, v121
	v_add_f32_e32 v122, v122, v123
	v_add_f32_e32 v124, v124, v125
	v_add_f32_e32 v126, v126, v127
	v_add_f32_e32 v120, v120, v122
	v_add_f32_e32 v124, v124, v126
	v_add_f32_e32 v136, v120, v124
	v_add_f32_e32 v128, v128, v129
	v_add_f32_e32 v130, v130, v131
	v_add_f32_e32 v132, v132, v133
	v_add_f32_e32 v134, v134, v135
	v_add_f32_e32 v128, v128, v130
	v_add_f32_e32 v132, v132, v134
	v_add_f32_e32 v137, v128, v132
	global_store_dwordx2 v7, v[136:137], s[48:49]
	v_add_u32_e32 v7, s64, v7
	s_add_i32 s6, s6, 1
	v_add_u32_e32 v146, 1, v146
	s_waitcnt lgkmcnt(0)
	ds_write_b32 v145, v146
	s_cmp_lt_u32 s6, 0xfe
	s_cbranch_scc1 .Lsc_G_loop
	s_sub_u32 s65, s6, 1
	s_mov_b32 s69, 0x100000

.Lsc_G_goz0:
	s_waitcnt vmcnt(10)
	v_lshlrev_b32_e32 v64, 16, v36
	v_and_b32_e32 v65, 0xffff0000, v36
	v_mul_f32_e32 v64, 0x3fb8aa3b, v64
	v_mul_f32_e32 v65, 0x3fb8aa3b, v65
	v_lshlrev_b32_e32 v66, 16, v37
	v_and_b32_e32 v67, 0xffff0000, v37
	v_mul_f32_e32 v66, 0x3fb8aa3b, v66
	v_mul_f32_e32 v67, 0x3fb8aa3b, v67
	v_lshlrev_b32_e32 v68, 16, v38
	v_and_b32_e32 v69, 0xffff0000, v38
	v_mul_f32_e32 v68, 0x3fb8aa3b, v68
	v_mul_f32_e32 v69, 0x3fb8aa3b, v69
	v_lshlrev_b32_e32 v70, 16, v39
	v_and_b32_e32 v71, 0xffff0000, v39
	v_mul_f32_e32 v70, 0x3fb8aa3b, v70
	v_mul_f32_e32 v71, 0x3fb8aa3b, v71
	ds_write_b128 v153, v[64:67]
	ds_write_b128 v153, v[68:71] offset:128
	s_waitcnt lgkmcnt(0)
	ds_read_b32 v124, v154 offset:0
	ds_read_b32 v125, v154 offset:256
	ds_read_b32 v126, v154 offset:512
	ds_read_b32 v127, v154 offset:768
	ds_read_b32 v128, v154 offset:1024
	ds_read_b32 v129, v154 offset:1280
	ds_read_b32 v130, v154 offset:1536
	ds_read_b32 v131, v154 offset:1792
	v_lshlrev_b32_e32 v108, 16, v32
	v_and_b32_e32 v109, 0xffff0000, v32
	v_lshlrev_b32_e32 v110, 16, v40
	v_and_b32_e32 v111, 0xffff0000, v40
	v_lshlrev_b32_e32 v96, 16, v28
	v_and_b32_e32 v97, 0xffff0000, v28
	v_pk_add_f32 v[112:113], v[110:111], -1.0 op_sel_hi:[1,0]
	v_pk_mul_f32 v[114:115], v[12:13], v[108:109]
	v_pk_fma_f32 v[112:113], v[20:21], v[112:113], 1.0 op_sel_hi:[1,1,0]
	v_pk_mul_f32 v[88:89], v[44:45], v[114:115] op_sel_hi:[0,1]
	v_pk_mul_f32 v[72:73], v[112:113], v[108:109]
	v_pk_mul_f32 v[80:81], v[88:89], v[110:111]
	v_lshlrev_b32_e32 v108, 16, v33
	v_and_b32_e32 v109, 0xffff0000, v33
	v_lshlrev_b32_e32 v110, 16, v41
	v_and_b32_e32 v111, 0xffff0000, v41
	v_lshlrev_b32_e32 v98, 16, v29
	v_and_b32_e32 v99, 0xffff0000, v29
	v_pk_add_f32 v[112:113], v[110:111], -1.0 op_sel_hi:[1,0]
	v_pk_mul_f32 v[114:115], v[14:15], v[108:109]
	v_pk_fma_f32 v[112:113], v[22:23], v[112:113], 1.0 op_sel_hi:[1,1,0]
	v_pk_mul_f32 v[90:91], v[44:45], v[114:115] op_sel_hi:[0,1]
	v_pk_mul_f32 v[74:75], v[112:113], v[108:109]
	v_pk_mul_f32 v[82:83], v[90:91], v[110:111]
	v_lshlrev_b32_e32 v108, 16, v34
	v_and_b32_e32 v109, 0xffff0000, v34
	v_lshlrev_b32_e32 v110, 16, v42
	v_and_b32_e32 v111, 0xffff0000, v42
	v_lshlrev_b32_e32 v100, 16, v30
	v_and_b32_e32 v101, 0xffff0000, v30
	v_pk_add_f32 v[112:113], v[110:111], -1.0 op_sel_hi:[1,0]
	v_pk_mul_f32 v[114:115], v[16:17], v[108:109]
	v_pk_fma_f32 v[112:113], v[24:25], v[112:113], 1.0 op_sel_hi:[1,1,0]
	v_pk_mul_f32 v[92:93], v[44:45], v[114:115] op_sel_hi:[0,1]
	v_pk_mul_f32 v[76:77], v[112:113], v[108:109]
	v_pk_mul_f32 v[84:85], v[92:93], v[110:111]
	v_lshlrev_b32_e32 v108, 16, v35
	v_and_b32_e32 v109, 0xffff0000, v35
	v_lshlrev_b32_e32 v110, 16, v43
	v_and_b32_e32 v111, 0xffff0000, v43
	v_lshlrev_b32_e32 v102, 16, v31
	v_and_b32_e32 v103, 0xffff0000, v31
	v_pk_add_f32 v[112:113], v[110:111], -1.0 op_sel_hi:[1,0]
	v_pk_mul_f32 v[114:115], v[18:19], v[108:109]
	v_pk_fma_f32 v[112:113], v[26:27], v[112:113], 1.0 op_sel_hi:[1,1,0]
	v_pk_mul_f32 v[94:95], v[44:45], v[114:115] op_sel_hi:[0,1]
	v_pk_mul_f32 v[78:79], v[112:113], v[108:109]
	v_pk_mul_f32 v[86:87], v[94:95], v[110:111]
	v_lshlrev_b32_e32 v104, 16, v45
	v_and_b32_e32 v105, 0xffff0000, v45
	s_waitcnt lgkmcnt(0)
	v_add_f32_e32 v125, v124, v125
	v_add_f32_e32 v126, v125, v126
	v_add_f32_e32 v127, v126, v127
	v_add_f32_e32 v128, v127, v128
	v_add_f32_e32 v129, v128, v129
	v_add_f32_e32 v130, v129, v130
	v_add_f32_e32 v131, v130, v131
	v_exp_f32_e64 v124, -v124
	v_exp_f32_e64 v125, -v125
	v_exp_f32_e64 v126, -v126
	v_exp_f32_e64 v127, -v127
	v_exp_f32_e64 v128, -v128
	v_exp_f32_e64 v129, -v129
	v_exp_f32_e64 v130, -v130
	v_exp_f32_e64 v131, -v131
	s_nop 0
	ds_write_b32 v155, v124 offset:256
	ds_write_b32 v155, v125 offset:512
	ds_write_b32 v155, v126 offset:768
	ds_write_b32 v155, v127 offset:1024
	ds_write_b32 v155, v128 offset:1280
	ds_write_b32 v155, v129 offset:1536
	ds_write_b32 v155, v130 offset:1792
	ds_write_b32 v155, v131 offset:2048
	ds_write_b32 v159, v131 offset:0
	s_waitcnt lgkmcnt(0)
	ds_read_b128 v[64:67], v153 offset:2048
	ds_read_b128 v[68:71], v153 offset:2176
	ds_read_b128 v[116:119], v153 offset:2304
	ds_read_b128 v[120:123], v153 offset:2432
	s_waitcnt lgkmcnt(0)
	v_rcp_f32_e32 v124, v116
	v_rcp_f32_e32 v125, v117
	v_rcp_f32_e32 v126, v118
	v_rcp_f32_e32 v127, v119
	v_rcp_f32_e32 v128, v120
	v_rcp_f32_e32 v129, v121
	v_rcp_f32_e32 v130, v122
	v_rcp_f32_e32 v131, v123
	s_nop 1
	v_pk_mul_f32 v[72:73], v[72:73], v[124:125]
	v_pk_mul_f32 v[80:81], v[80:81], v[124:125]
	v_pk_mul_f32 v[88:89], v[88:89], v[64:65]
	v_pk_mul_f32 v[96:97], v[96:97], v[116:117]
	v_pk_mul_f32 v[74:75], v[74:75], v[126:127]
	v_pk_mul_f32 v[82:83], v[82:83], v[126:127]
	v_pk_mul_f32 v[90:91], v[90:91], v[66:67]
	v_pk_mul_f32 v[98:99], v[98:99], v[118:119]
	v_pk_mul_f32 v[76:77], v[76:77], v[128:129]
	v_pk_mul_f32 v[84:85], v[84:85], v[128:129]
	v_pk_mul_f32 v[92:93], v[92:93], v[68:69]
	v_pk_mul_f32 v[100:101], v[100:101], v[120:121]
	v_pk_mul_f32 v[78:79], v[78:79], v[130:131]
	v_pk_mul_f32 v[86:87], v[86:87], v[130:131]
	v_pk_mul_f32 v[94:95], v[94:95], v[70:71]
	v_pk_mul_f32 v[102:103], v[102:103], v[122:123]
	ds_write_b128 v8, v[72:75] offset:0
	ds_write_b128 v8, v[76:79] offset:128
	ds_write_b128 v8, v[80:83] offset:256
	ds_write_b128 v8, v[84:87] offset:384
	ds_write2_b32 v138, v96, v97 offset0:1 offset1:3
	ds_write2_b32 v139, v88, v89 offset0:0 offset1:2
	ds_write2_b32 v138, v98, v99 offset0:65 offset1:67
	ds_write2_b32 v139, v90, v91 offset0:64 offset1:66
	ds_write2_b32 v138, v100, v101 offset0:33 offset1:35
	ds_write2_b32 v139, v92, v93 offset0:32 offset1:34
	ds_write2_b32 v138, v102, v103 offset0:97 offset1:99
	ds_write2_b32 v139, v94, v95 offset0:96 offset1:98
	ds_write2_b32 v142, v104, v105 offset1:36
	s_and_saveexec_b64 s[68:69], s[12:13]
	ds_write_b128 v158, v[88:91] offset:0
	ds_write_b128 v158, v[92:95] offset:128
	s_mov_b64 exec, s[68:69]
	ds_read_b128 v[120:123], v11 offset:0
	ds_read_b128 v[124:127], v11 offset:16
	ds_read_b128 v[128:131], v11 offset:32
	ds_read_b128 v[132:135], v11 offset:48
	s_waitcnt lgkmcnt(0)
	v_add_f32_e32 v120, v120, v121
	v_add_f32_e32 v122, v122, v123
	v_add_f32_e32 v124, v124, v125
	v_add_f32_e32 v126, v126, v127
	v_add_f32_e32 v120, v120, v122
	v_add_f32_e32 v124, v124, v126
	v_add_f32_e32 v136, v120, v124
	v_add_f32_e32 v128, v128, v129
	v_add_f32_e32 v130, v130, v131
	v_add_f32_e32 v132, v132, v133
	v_add_f32_e32 v134, v134, v135
	v_add_f32_e32 v128, v128, v130
	v_add_f32_e32 v132, v132, v134
	v_add_f32_e32 v137, v128, v132
	global_store_dwordx2 v7, v[136:137], s[48:49]
	v_add_u32_e32 v7, s64, v7
	s_add_i32 s6, s6, 1
	v_add_u32_e32 v146, 1, v146
	s_waitcnt lgkmcnt(0)
	ds_write_b32 v145, v146
	s_sub_u32 s65, s6, 1
	s_mov_b32 s69, 0x100000

.Lsc_G_goz1:
	s_waitcnt vmcnt(0)
	v_lshlrev_b32_e32 v64, 16, v54
	v_and_b32_e32 v65, 0xffff0000, v54
	v_mul_f32_e32 v64, 0x3fb8aa3b, v64
	v_mul_f32_e32 v65, 0x3fb8aa3b, v65
	v_lshlrev_b32_e32 v66, 16, v55
	v_and_b32_e32 v67, 0xffff0000, v55
	v_mul_f32_e32 v66, 0x3fb8aa3b, v66
	v_mul_f32_e32 v67, 0x3fb8aa3b, v67
	v_lshlrev_b32_e32 v68, 16, v56
	v_and_b32_e32 v69, 0xffff0000, v56
	v_mul_f32_e32 v68, 0x3fb8aa3b, v68
	v_mul_f32_e32 v69, 0x3fb8aa3b, v69
	v_lshlrev_b32_e32 v70, 16, v57
	v_and_b32_e32 v71, 0xffff0000, v57
	v_mul_f32_e32 v70, 0x3fb8aa3b, v70
	v_mul_f32_e32 v71, 0x3fb8aa3b, v71
	ds_write_b128 v153, v[64:67]
	ds_write_b128 v153, v[68:71] offset:128
	s_waitcnt lgkmcnt(0)
	ds_read_b32 v124, v154 offset:0
	ds_read_b32 v125, v154 offset:256
	ds_read_b32 v126, v154 offset:512
	ds_read_b32 v127, v154 offset:768
	ds_read_b32 v128, v154 offset:1024
	ds_read_b32 v129, v154 offset:1280
	ds_read_b32 v130, v154 offset:1536
	ds_read_b32 v131, v154 offset:1792
	v_lshlrev_b32_e32 v108, 16, v50
	v_and_b32_e32 v109, 0xffff0000, v50
	v_lshlrev_b32_e32 v110, 16, v58
	v_and_b32_e32 v111, 0xffff0000, v58
	v_lshlrev_b32_e32 v96, 16, v46
	v_and_b32_e32 v97, 0xffff0000, v46
	v_pk_add_f32 v[112:113], v[110:111], -1.0 op_sel_hi:[1,0]
	v_pk_mul_f32 v[114:115], v[12:13], v[108:109]
	v_pk_fma_f32 v[112:113], v[20:21], v[112:113], 1.0 op_sel_hi:[1,1,0]
	v_pk_mul_f32 v[88:89], v[62:63], v[114:115] op_sel_hi:[0,1]
	v_pk_mul_f32 v[72:73], v[112:113], v[108:109]
	v_pk_mul_f32 v[80:81], v[88:89], v[110:111]
	v_lshlrev_b32_e32 v108, 16, v51
	v_and_b32_e32 v109, 0xffff0000, v51
	v_lshlrev_b32_e32 v110, 16, v59
	v_and_b32_e32 v111, 0xffff0000, v59
	v_lshlrev_b32_e32 v98, 16, v47
	v_and_b32_e32 v99, 0xffff0000, v47
	v_pk_add_f32 v[112:113], v[110:111], -1.0 op_sel_hi:[1,0]
	v_pk_mul_f32 v[114:115], v[14:15], v[108:109]
	v_pk_fma_f32 v[112:113], v[22:23], v[112:113], 1.0 op_sel_hi:[1,1,0]
	v_pk_mul_f32 v[90:91], v[62:63], v[114:115] op_sel_hi:[0,1]
	v_pk_mul_f32 v[74:75], v[112:113], v[108:109]
	v_pk_mul_f32 v[82:83], v[90:91], v[110:111]
	v_lshlrev_b32_e32 v108, 16, v52
	v_and_b32_e32 v109, 0xffff0000, v52
	v_lshlrev_b32_e32 v110, 16, v60
	v_and_b32_e32 v111, 0xffff0000, v60
	v_lshlrev_b32_e32 v100, 16, v48
	v_and_b32_e32 v101, 0xffff0000, v48
	v_pk_add_f32 v[112:113], v[110:111], -1.0 op_sel_hi:[1,0]
	v_pk_mul_f32 v[114:115], v[16:17], v[108:109]
	v_pk_fma_f32 v[112:113], v[24:25], v[112:113], 1.0 op_sel_hi:[1,1,0]
	v_pk_mul_f32 v[92:93], v[62:63], v[114:115] op_sel_hi:[0,1]
	v_pk_mul_f32 v[76:77], v[112:113], v[108:109]
	v_pk_mul_f32 v[84:85], v[92:93], v[110:111]
	v_lshlrev_b32_e32 v108, 16, v53
	v_and_b32_e32 v109, 0xffff0000, v53
	v_lshlrev_b32_e32 v110, 16, v61
	v_and_b32_e32 v111, 0xffff0000, v61
	v_lshlrev_b32_e32 v102, 16, v49
	v_and_b32_e32 v103, 0xffff0000, v49
	v_pk_add_f32 v[112:113], v[110:111], -1.0 op_sel_hi:[1,0]
	v_pk_mul_f32 v[114:115], v[18:19], v[108:109]
	v_pk_fma_f32 v[112:113], v[26:27], v[112:113], 1.0 op_sel_hi:[1,1,0]
	v_pk_mul_f32 v[94:95], v[62:63], v[114:115] op_sel_hi:[0,1]
	v_pk_mul_f32 v[78:79], v[112:113], v[108:109]
	v_pk_mul_f32 v[86:87], v[94:95], v[110:111]
	v_lshlrev_b32_e32 v104, 16, v63
	v_and_b32_e32 v105, 0xffff0000, v63
	s_waitcnt lgkmcnt(0)
	v_add_f32_e32 v125, v124, v125
	v_add_f32_e32 v126, v125, v126
	v_add_f32_e32 v127, v126, v127
	v_add_f32_e32 v128, v127, v128
	v_add_f32_e32 v129, v128, v129
	v_add_f32_e32 v130, v129, v130
	v_add_f32_e32 v131, v130, v131
	v_exp_f32_e64 v124, -v124
	v_exp_f32_e64 v125, -v125
	v_exp_f32_e64 v126, -v126
	v_exp_f32_e64 v127, -v127
	v_exp_f32_e64 v128, -v128
	v_exp_f32_e64 v129, -v129
	v_exp_f32_e64 v130, -v130
	v_exp_f32_e64 v131, -v131
	s_nop 0
	ds_write_b32 v155, v124 offset:256
	ds_write_b32 v155, v125 offset:512
	ds_write_b32 v155, v126 offset:768
	ds_write_b32 v155, v127 offset:1024
	ds_write_b32 v155, v128 offset:1280
	ds_write_b32 v155, v129 offset:1536
	ds_write_b32 v155, v130 offset:1792
	ds_write_b32 v155, v131 offset:2048
	ds_write_b32 v159, v131 offset:34816
	s_waitcnt lgkmcnt(0)
	ds_read_b128 v[64:67], v153 offset:2048
	ds_read_b128 v[68:71], v153 offset:2176
	ds_read_b128 v[116:119], v153 offset:2304
	ds_read_b128 v[120:123], v153 offset:2432
	s_waitcnt lgkmcnt(0)
	v_rcp_f32_e32 v124, v116
	v_rcp_f32_e32 v125, v117
	v_rcp_f32_e32 v126, v118
	v_rcp_f32_e32 v127, v119
	v_rcp_f32_e32 v128, v120
	v_rcp_f32_e32 v129, v121
	v_rcp_f32_e32 v130, v122
	v_rcp_f32_e32 v131, v123
	s_nop 1
	v_pk_mul_f32 v[72:73], v[72:73], v[124:125]
	v_pk_mul_f32 v[80:81], v[80:81], v[124:125]
	v_pk_mul_f32 v[88:89], v[88:89], v[64:65]
	v_pk_mul_f32 v[96:97], v[96:97], v[116:117]
	v_pk_mul_f32 v[74:75], v[74:75], v[126:127]
	v_pk_mul_f32 v[82:83], v[82:83], v[126:127]
	v_pk_mul_f32 v[90:91], v[90:91], v[66:67]
	v_pk_mul_f32 v[98:99], v[98:99], v[118:119]
	v_pk_mul_f32 v[76:77], v[76:77], v[128:129]
	v_pk_mul_f32 v[84:85], v[84:85], v[128:129]
	v_pk_mul_f32 v[92:93], v[92:93], v[68:69]
	v_pk_mul_f32 v[100:101], v[100:101], v[120:121]
	v_pk_mul_f32 v[78:79], v[78:79], v[130:131]
	v_pk_mul_f32 v[86:87], v[86:87], v[130:131]
	v_pk_mul_f32 v[94:95], v[94:95], v[70:71]
	v_pk_mul_f32 v[102:103], v[102:103], v[122:123]
	ds_write_b128 v8, v[72:75] offset:34816
	ds_write_b128 v8, v[76:79] offset:34944
	ds_write_b128 v8, v[80:83] offset:35072
	ds_write_b128 v8, v[84:87] offset:35200
	ds_write2_b32 v140, v96, v97 offset0:1 offset1:3
	ds_write2_b32 v141, v88, v89 offset0:0 offset1:2
	ds_write2_b32 v140, v98, v99 offset0:65 offset1:67
	ds_write2_b32 v141, v90, v91 offset0:64 offset1:66
	ds_write2_b32 v140, v100, v101 offset0:33 offset1:35
	ds_write2_b32 v141, v92, v93 offset0:32 offset1:34
	ds_write2_b32 v140, v102, v103 offset0:97 offset1:99
	ds_write2_b32 v141, v94, v95 offset0:96 offset1:98
	ds_write2_b32 v143, v104, v105 offset1:36
	s_and_saveexec_b64 s[68:69], s[12:13]
	ds_write_b128 v158, v[88:91] offset:34816
	ds_write_b128 v158, v[92:95] offset:34944
	s_mov_b64 exec, s[68:69]
	ds_read_b128 v[120:123], v11 offset:16384
	ds_read_b128 v[124:127], v11 offset:16400
	ds_read_b128 v[128:131], v11 offset:16416
	ds_read_b128 v[132:135], v11 offset:16432
	s_waitcnt lgkmcnt(0)
	v_add_f32_e32 v120, v120, v121
	v_add_f32_e32 v122, v122, v123
	v_add_f32_e32 v124, v124, v125
	v_add_f32_e32 v126, v126, v127
	v_add_f32_e32 v120, v120, v122
	v_add_f32_e32 v124, v124, v126
	v_add_f32_e32 v136, v120, v124
	v_add_f32_e32 v128, v128, v129
	v_add_f32_e32 v130, v130, v131
	v_add_f32_e32 v132, v132, v133
	v_add_f32_e32 v134, v134, v135
	v_add_f32_e32 v128, v128, v130
	v_add_f32_e32 v132, v132, v134
	v_add_f32_e32 v137, v128, v132
	global_store_dwordx2 v7, v[136:137], s[48:49]
	v_add_u32_e32 v7, s64, v7
	s_add_i32 s6, s6, 1
	v_add_u32_e32 v146, 1, v146
	s_waitcnt lgkmcnt(0)
	ds_write_b32 v145, v146
	s_sub_u32 s65, s6, 1
	s_mov_b32 s69, 0x100000
